# seam weight conversion queue + nt on f32 weight loads and on bf16 weight-copy stores
# baseline (speedup 1.0000x reference)
; __host__ __device__ __forceinline__ int blk_off(int r, int c) { const int rr = r & 127; return (r >> 7) * 8192 + (((rr >> 4) * 2 + (c >> 5)) * 512) + (rr & 15) * 32 + (c & 31); }
; __device__ __forceinline__ unsigned cvt_pk_bf16(float lo, float hi) { unsigned r; asm volatile("v_cvt_pk_bf16_f32 %0, %1, %2" : "=v"(r) : "v"(lo), "v"(hi)); return r; }
; __device__ __forceinline__ void titem_process(const TItem& d, const f32x4 (&v)[16], const float (&gg)[16], int lane) {
;     const int n0 = d.perm >> 1;
; #pragma unroll
;     for (int j = 0; j < 4; ++j) { const int n = n0 + 4 * (lane & 15) + j, nr = (d.perm & 1) ? win_row(n) : n;
;         const int w32 = nr & 31, nrs = (nr & 255 & ~31) + 16 * ((w32 >> 2) & 1) + 4 * (w32 >> 3) + (w32 & 3);
;         bf16* rowp = d.dst + (size_t)(nr >> 8) * (d.K >> 6) * (256 * 64);
; #pragma unroll
;         for (int h = 0; h < 2; ++h) { v4u o;
;             o.x = pg8::cvt_pk_bf16(v[8 * h + 0][j] * gg[8 * h + 0], v[8 * h + 1][j] * gg[8 * h + 1]); o.y = pg8::cvt_pk_bf16(v[8 * h + 2][j] * gg[8 * h + 2], v[8 * h + 3][j] * gg[8 * h + 3]);
;             o.z = pg8::cvt_pk_bf16(v[8 * h + 4][j] * gg[8 * h + 4], v[8 * h + 5][j] * gg[8 * h + 5]); o.w = pg8::cvt_pk_bf16(v[8 * h + 6][j] * gg[8 * h + 6], v[8 * h + 7][j] * gg[8 * h + 7]);
;             *(v4u*)(rowp + pg8::blk_off(nrs, 8 * (lane >> 4) + 32 * h)) = o; } }
.LBB0_101:
	v_and_b32_e32 v188, 0x60, v130
	v_lshlrev_b32_e32 v189, 2, v130
	s_ashr_i32 s4, s3, 6
	v_and_or_b32 v194, v189, 16, v188
	v_lshrrev_b32_e32 v188, 1, v130
	v_and_b32_e32 v189, 3, v130
	v_ashrrev_i32_e32 v191, 8, v130
	s_ashr_i32 s5, s4, 31
	v_and_or_b32 v190, v188, 12, v189
	v_ashrrev_i32_e32 v188, 31, v191
	s_lshl_b64 s[36:37], s[4:5], 15
	v_lshlrev_b32_e32 v130, 6, v130
	v_mul_lo_u32 v195, s36, v188
	s_lshr_b64 s[4:5], s[4:5], 17
	v_mov_b64_e32 v[188:189], s[0:1]
	v_and_b32_e32 v130, 0x2000, v130
	v_mul_i32_i24_e32 v196, s4, v191
	v_mad_u64_u32 v[192:193], s[4:5], s36, v191, v[188:189]
	v_lshl_or_b32 v130, v190, 5, v130
	s_waitcnt vmcnt(15)
	v_mul_f32_e32 v188, v162, v2
	s_waitcnt vmcnt(14)
	v_mul_f32_e32 v189, v161, v6
	v_lshlrev_b32_e32 v194, 6, v194
	v_cvt_pk_bf16_f32 v188, v188, v189
	s_waitcnt vmcnt(13)
	v_mul_f32_e32 v189, v164, v10
	s_waitcnt vmcnt(12)
	v_mul_f32_e32 v190, v163, v14
	v_or3_b32 v130, v130, v194, v179
	v_add3_u32 v193, v196, v193, v195
	v_cvt_pk_bf16_f32 v189, v189, v190
	s_waitcnt vmcnt(11)
	v_mul_f32_e32 v190, v166, v18
	s_waitcnt vmcnt(10)
	v_mul_f32_e32 v191, v165, v22
	v_lshlrev_b32_e32 v130, 1, v130
	v_cvt_pk_bf16_f32 v190, v190, v191
	s_waitcnt vmcnt(9)
	v_mul_f32_e32 v191, v168, v26
	v_lshl_add_u64 v[192:193], v[192:193], 0, v[130:131]
	s_waitcnt vmcnt(8)
	v_mul_f32_e32 v195, v167, v30
	v_cvt_pk_bf16_f32 v191, v191, v195
	global_store_dwordx4 v[192:193], v[188:191], off nt
	s_waitcnt vmcnt(8)
	v_mul_f32_e32 v130, v171, v34
	s_andn2_b64 vcc, exec, s[38:39]
	s_waitcnt vmcnt(7)
	v_mul_f32_e32 v188, v170, v38
	v_cvt_pk_bf16_f32 v188, v130, v188
	s_waitcnt vmcnt(6)
	v_mul_f32_e32 v130, v173, v42
	s_waitcnt vmcnt(5)
	v_mul_f32_e32 v189, v172, v46
	v_cvt_pk_bf16_f32 v189, v130, v189
	s_waitcnt vmcnt(4)
	v_mul_f32_e32 v130, v175, v50
	s_waitcnt vmcnt(3)
	v_mul_f32_e32 v190, v174, v54
	v_cvt_pk_bf16_f32 v190, v130, v190
	s_waitcnt vmcnt(2)
	v_mul_f32_e32 v130, v178, v58
	s_waitcnt vmcnt(1)
	v_mul_f32_e32 v191, v176, v62
	v_cvt_pk_bf16_f32 v191, v130, v191
	v_cndmask_b32_e64 v130, 0, 1, s[38:39]
	v_cmp_ne_u32_e64 s[4:5], 1, v130
	v_add_u32_e32 v130, 1, v187
	global_store_dwordx4 v[192:193], v[188:191], off offset:1024 nt
	s_cbranch_vccnz .LBB0_107
	v_cmp_gt_i32_e32 vcc, s52, v187
	s_and_saveexec_b64 s[38:39], vcc
	s_xor_b64 s[38:39], exec, s[38:39]
	v_lshlrev_b32_e32 v188, 2, v130
	v_lshrrev_b32_e32 v189, 1, v130
	v_and_b32_e32 v188, 0x80, v188
	v_and_b32_e32 v189, 0x60, v189
	v_and_b32_e32 v130, 0xffffff1f, v130
	v_or3_b32 v130, v188, v130, v189
	s_andn2_saveexec_b64 s[38:39], s[38:39]
	v_cmp_lt_u32_e32 vcc, s54, v130
	s_nop 1
	v_cndmask_b32_e32 v188, v180, v181, vcc
	v_add_lshl_u32 v188, v188, v130, 1
	v_and_b32_e32 v188, 0xffffff00, v188
	v_cndmask_b32_e32 v189, 0, v182, vcc
	v_and_b32_e32 v130, 0x7f, v130
	v_or3_b32 v130, v188, v189, v130
	v_add_u32_e32 v130, 0x1000, v130
	s_or_b64 exec, exec, s[38:39]
.LBB0_107:
	s_nop 0
	v_and_b32_e32 v188, 0x60, v130
	v_lshlrev_b32_e32 v189, 2, v130
	v_and_or_b32 v194, v189, 16, v188
	v_lshrrev_b32_e32 v188, 1, v130
	v_and_b32_e32 v189, 3, v130
	v_ashrrev_i32_e32 v191, 8, v130
	v_and_or_b32 v190, v188, 12, v189
	v_ashrrev_i32_e32 v188, 31, v191
	v_lshlrev_b32_e32 v130, 6, v130
	v_mul_lo_u32 v195, s36, v188
	v_mov_b64_e32 v[188:189], s[0:1]
	v_and_b32_e32 v130, 0x2000, v130
	v_mad_u64_u32 v[192:193], s[38:39], s36, v191, v[188:189]
	v_lshl_or_b32 v130, v190, 5, v130
	v_mul_f32_e32 v188, v162, v3
	v_mul_f32_e32 v189, v161, v7
	v_lshlrev_b32_e32 v194, 6, v194
	v_mul_i32_i24_e32 v196, s37, v191
	v_cvt_pk_bf16_f32 v188, v188, v189
	v_mul_f32_e32 v189, v164, v11
	v_mul_f32_e32 v190, v163, v15
	v_or3_b32 v130, v130, v194, v179
	v_add3_u32 v193, v196, v193, v195
	v_cvt_pk_bf16_f32 v189, v189, v190
	v_mul_f32_e32 v190, v166, v19
	v_mul_f32_e32 v191, v165, v23
	v_lshlrev_b32_e32 v130, 1, v130
	v_cvt_pk_bf16_f32 v190, v190, v191
	v_mul_f32_e32 v191, v168, v27
	v_lshl_add_u64 v[192:193], v[192:193], 0, v[130:131]
	v_mul_f32_e32 v195, v167, v31
	v_cvt_pk_bf16_f32 v191, v191, v195
	global_store_dwordx4 v[192:193], v[188:191], off nt
	v_mul_f32_e32 v130, v171, v35
	s_and_b64 vcc, exec, s[4:5]
	v_mul_f32_e32 v188, v170, v39
	v_cvt_pk_bf16_f32 v188, v130, v188
	v_mul_f32_e32 v130, v173, v43
	v_mul_f32_e32 v189, v172, v47
	v_cvt_pk_bf16_f32 v189, v130, v189
	v_mul_f32_e32 v130, v175, v51
	v_mul_f32_e32 v190, v174, v55
	v_cvt_pk_bf16_f32 v190, v130, v190
	v_mul_f32_e32 v130, v178, v59
	v_mul_f32_e32 v191, v176, v63
	v_cvt_pk_bf16_f32 v191, v130, v191
	v_add_u32_e32 v130, 2, v187
	global_store_dwordx4 v[192:193], v[188:191], off offset:1024 nt
	s_cbranch_vccnz .LBB0_113
	v_cmp_gt_i32_e32 vcc, s55, v187
	s_and_saveexec_b64 s[38:39], vcc
	s_xor_b64 s[38:39], exec, s[38:39]
	v_lshlrev_b32_e32 v188, 2, v130
	v_lshrrev_b32_e32 v189, 1, v130
	v_and_b32_e32 v188, 0x80, v188
	v_and_b32_e32 v189, 0x60, v189
	v_and_b32_e32 v130, 0xffffff1f, v130
	v_or3_b32 v130, v188, v130, v189
	s_andn2_saveexec_b64 s[38:39], s[38:39]
	v_cmp_lt_u32_e32 vcc, s54, v130
	s_nop 1
	v_cndmask_b32_e32 v188, v180, v181, vcc
	v_add_lshl_u32 v188, v188, v130, 1
	v_and_b32_e32 v188, 0xffffff00, v188
	v_cndmask_b32_e32 v189, 0, v182, vcc
	v_and_b32_e32 v130, 0x7f, v130
	v_or3_b32 v130, v188, v189, v130
	v_add_u32_e32 v130, 0x1000, v130
	s_or_b64 exec, exec, s[38:39]
; __host__ __device__ __forceinline__ int blk_off(int r, int c) { const int rr = r & 127; return (r >> 7) * 8192 + (((rr >> 4) * 2 + (c >> 5)) * 512) + (rr & 15) * 32 + (c & 31); }
; __device__ __forceinline__ unsigned cvt_pk_bf16(float lo, float hi) { unsigned r; asm volatile("v_cvt_pk_bf16_f32 %0, %1, %2" : "=v"(r) : "v"(lo), "v"(hi)); return r; }
; __device__ __forceinline__ void titem_process(const TItem& d, const f32x4 (&v)[16], const float (&gg)[16], int lane) {
;     const int n0 = d.perm >> 1;
; #pragma unroll
;     for (int j = 0; j < 4; ++j) { const int n = n0 + 4 * (lane & 15) + j, nr = (d.perm & 1) ? win_row(n) : n;
;         const int w32 = nr & 31, nrs = (nr & 255 & ~31) + 16 * ((w32 >> 2) & 1) + 4 * (w32 >> 3) + (w32 & 3);
;         bf16* rowp = d.dst + (size_t)(nr >> 8) * (d.K >> 6) * (256 * 64);
; #pragma unroll
;         for (int h = 0; h < 2; ++h) { v4u o;
;             o.x = pg8::cvt_pk_bf16(v[8 * h + 0][j] * gg[8 * h + 0], v[8 * h + 1][j] * gg[8 * h + 1]); o.y = pg8::cvt_pk_bf16(v[8 * h + 2][j] * gg[8 * h + 2], v[8 * h + 3][j] * gg[8 * h + 3]);
;             o.z = pg8::cvt_pk_bf16(v[8 * h + 4][j] * gg[8 * h + 4], v[8 * h + 5][j] * gg[8 * h + 5]); o.w = pg8::cvt_pk_bf16(v[8 * h + 6][j] * gg[8 * h + 6], v[8 * h + 7][j] * gg[8 * h + 7]);
;             *(v4u*)(rowp + pg8::blk_off(nrs, 8 * (lane >> 4) + 32 * h)) = o; } }
.LBB0_113:
	s_nop 0
	v_and_b32_e32 v188, 0x60, v130
	v_lshlrev_b32_e32 v189, 2, v130
	v_and_or_b32 v194, v189, 16, v188
	v_lshrrev_b32_e32 v188, 1, v130
	v_and_b32_e32 v189, 3, v130
	v_ashrrev_i32_e32 v191, 8, v130
	v_and_or_b32 v190, v188, 12, v189
	v_ashrrev_i32_e32 v188, 31, v191
	v_lshlrev_b32_e32 v130, 6, v130
	v_mul_lo_u32 v195, s36, v188
	v_mov_b64_e32 v[188:189], s[0:1]
	v_and_b32_e32 v130, 0x2000, v130
	v_mad_u64_u32 v[192:193], s[38:39], s36, v191, v[188:189]
	v_lshl_or_b32 v130, v190, 5, v130
	v_mul_f32_e32 v188, v162, v4
	v_mul_f32_e32 v189, v161, v8
	v_lshlrev_b32_e32 v194, 6, v194
	v_mul_i32_i24_e32 v196, s37, v191
	v_cvt_pk_bf16_f32 v188, v188, v189
	v_mul_f32_e32 v189, v164, v12
	v_mul_f32_e32 v190, v163, v16
	v_or3_b32 v130, v130, v194, v179
	v_add3_u32 v193, v196, v193, v195
	v_cvt_pk_bf16_f32 v189, v189, v190
	v_mul_f32_e32 v190, v166, v20
	v_mul_f32_e32 v191, v165, v24
	v_lshlrev_b32_e32 v130, 1, v130
	v_cvt_pk_bf16_f32 v190, v190, v191
	v_mul_f32_e32 v191, v168, v28
	v_lshl_add_u64 v[192:193], v[192:193], 0, v[130:131]
	v_mul_f32_e32 v195, v167, v32
	v_cvt_pk_bf16_f32 v191, v191, v195
	global_store_dwordx4 v[192:193], v[188:191], off nt
	v_mul_f32_e32 v130, v171, v36
	s_and_b64 vcc, exec, s[4:5]
	v_mul_f32_e32 v188, v170, v40
	v_cvt_pk_bf16_f32 v188, v130, v188
	v_mul_f32_e32 v130, v173, v44
	v_mul_f32_e32 v189, v172, v48
	v_cvt_pk_bf16_f32 v189, v130, v189
	v_mul_f32_e32 v130, v175, v52
	v_mul_f32_e32 v190, v174, v56
	v_cvt_pk_bf16_f32 v190, v130, v190
	v_mul_f32_e32 v130, v178, v60
	v_mul_f32_e32 v191, v176, v64
	v_cvt_pk_bf16_f32 v191, v130, v191
	v_add_u32_e32 v130, 3, v187
	global_store_dwordx4 v[192:193], v[188:191], off offset:1024 nt
	s_cbranch_vccnz .LBB0_119
	v_cmp_gt_i32_e32 vcc, s56, v187
	s_and_saveexec_b64 s[4:5], vcc
	s_xor_b64 s[4:5], exec, s[4:5]
	v_lshlrev_b32_e32 v187, 2, v130
	v_lshrrev_b32_e32 v188, 1, v130
	v_and_b32_e32 v187, 0x80, v187
	v_and_b32_e32 v188, 0x60, v188
	v_and_b32_e32 v130, 0xffffff1f, v130
	v_or3_b32 v130, v187, v130, v188
	s_andn2_saveexec_b64 s[4:5], s[4:5]
	v_cmp_lt_u32_e32 vcc, s54, v130
	s_nop 1
	v_cndmask_b32_e32 v187, v180, v181, vcc
	v_add_lshl_u32 v187, v187, v130, 1
	v_and_b32_e32 v187, 0xffffff00, v187
	v_cndmask_b32_e32 v188, 0, v182, vcc
	v_and_b32_e32 v130, 0x7f, v130
	v_or3_b32 v130, v187, v188, v130
	v_add_u32_e32 v130, 0x1000, v130
	s_or_b64 exec, exec, s[4:5]
.LBB0_119:
	v_and_b32_e32 v187, 0x60, v130
	v_lshlrev_b32_e32 v188, 2, v130
	v_and_or_b32 v187, v188, 16, v187
	v_lshrrev_b32_e32 v188, 1, v130
	v_and_b32_e32 v189, 3, v130
	v_ashrrev_i32_e32 v191, 8, v130
	v_and_or_b32 v190, v188, 12, v189
	v_ashrrev_i32_e32 v188, 31, v191
	v_lshlrev_b32_e32 v130, 6, v130
	v_mul_lo_u32 v194, s36, v188
	v_mov_b64_e32 v[188:189], s[0:1]
	v_and_b32_e32 v130, 0x2000, v130
	v_mad_u64_u32 v[192:193], s[4:5], s36, v191, v[188:189]
	v_lshl_or_b32 v130, v190, 5, v130
	v_mul_f32_e32 v188, v162, v5
	v_mul_f32_e32 v189, v161, v9
	v_lshlrev_b32_e32 v187, 6, v187
	v_mul_i32_i24_e32 v195, s37, v191
	v_cvt_pk_bf16_f32 v188, v188, v189
	v_mul_f32_e32 v189, v164, v13
	v_mul_f32_e32 v190, v163, v17
	v_or3_b32 v130, v130, v187, v179
	v_add3_u32 v193, v195, v193, v194
	v_cvt_pk_bf16_f32 v189, v189, v190
	v_mul_f32_e32 v190, v166, v21
	v_mul_f32_e32 v191, v165, v25
	v_lshlrev_b32_e32 v130, 1, v130
	v_cvt_pk_bf16_f32 v190, v190, v191
	v_mul_f32_e32 v191, v168, v29
	v_lshl_add_u64 v[192:193], v[192:193], 0, v[130:131]
	v_mul_f32_e32 v130, v171, v37
	v_mul_f32_e32 v187, v170, v41
	v_mul_f32_e32 v194, v167, v33
	v_cvt_pk_bf16_f32 v191, v191, v194
	global_store_dwordx4 v[192:193], v[188:191], off nt
	s_andn2_b64 vcc, exec, s[30:31]
	s_nop 0
	v_cvt_pk_bf16_f32 v188, v130, v187
	v_mul_f32_e32 v130, v173, v45
	v_mul_f32_e32 v187, v172, v49
	v_cvt_pk_bf16_f32 v189, v130, v187
	v_mul_f32_e32 v130, v175, v53
	v_mul_f32_e32 v187, v174, v57
	v_cvt_pk_bf16_f32 v190, v130, v187
	v_mul_f32_e32 v130, v178, v61
	v_mul_f32_e32 v187, v176, v65
	v_cvt_pk_bf16_f32 v191, v130, v187
	global_store_dwordx4 v[192:193], v[188:191], off offset:1024 nt
	s_cbranch_vccnz .LBB0_57
	v_mov_b64_e32 v[62:63], v[126:127]
	v_mov_b64_e32 v[58:59], v[118:119]
	v_mov_b64_e32 v[54:55], v[122:123]
	v_mov_b64_e32 v[50:51], v[110:111]
	v_mov_b64_e32 v[46:47], v[114:115]
	v_mov_b64_e32 v[42:43], v[102:103]
	v_mov_b64_e32 v[38:39], v[106:107]
	v_mov_b64_e32 v[34:35], v[94:95]
	v_mov_b64_e32 v[30:31], v[98:99]
	v_mov_b64_e32 v[26:27], v[86:87]
	v_mov_b64_e32 v[22:23], v[90:91]
	v_mov_b64_e32 v[18:19], v[78:79]
	v_mov_b64_e32 v[14:15], v[82:83]
	v_mov_b64_e32 v[10:11], v[70:71]
	v_mov_b64_e32 v[6:7], v[74:75]
	v_mov_b64_e32 v[2:3], v[66:67]
	v_mov_b64_e32 v[64:65], v[128:129]
	v_mov_b64_e32 v[60:61], v[120:121]
	v_mov_b64_e32 v[56:57], v[124:125]
	v_mov_b64_e32 v[52:53], v[112:113]
	v_mov_b64_e32 v[48:49], v[116:117]
	v_mov_b64_e32 v[44:45], v[104:105]
	v_mov_b64_e32 v[40:41], v[108:109]
	v_mov_b64_e32 v[36:37], v[96:97]
	v_mov_b64_e32 v[32:33], v[100:101]
	v_mov_b64_e32 v[28:29], v[88:89]
	v_mov_b64_e32 v[24:25], v[92:93]
	v_mov_b64_e32 v[20:21], v[80:81]
	v_mov_b64_e32 v[16:17], v[84:85]
	v_mov_b64_e32 v[12:13], v[72:73]
	v_mov_b64_e32 v[8:9], v[76:77]
	v_mov_b64_e32 v[4:5], v[68:69]
	s_mov_b64 s[0:1], s[34:35]
	s_mov_b32 s3, s58
	s_mov_b32 s23, s40
	v_mov_b32_e32 v162, v132
	v_mov_b32_e32 v161, v133
	v_mov_b32_e32 v164, v134
	v_mov_b32_e32 v163, v135
	v_mov_b32_e32 v166, v136
	v_mov_b32_e32 v165, v137
	v_mov_b32_e32 v168, v183
	v_mov_b32_e32 v167, v184
	v_mov_b32_e32 v171, v138
	v_mov_b32_e32 v170, v139
	v_mov_b32_e32 v173, v140
	v_mov_b32_e32 v172, v141
	v_mov_b32_e32 v175, v142
	v_mov_b32_e32 v174, v143
	v_mov_b32_e32 v178, v185
	v_mov_b32_e32 v176, v186
	s_branch .LBB0_57
